# MLA attention loop software-pipelined by hand: QK MFMAs of key tile i+1 issued under softmax/PV of tile i; K tile stored to LDS one step early
# baseline (speedup 1.0000x reference)
; #define MFMA(a, b, c) __builtin_amdgcn_mfma_f32_32x32x16_bf16((a), (b), (c), 0, 0, 0)
; template <int DQK>
; DI void attn_tile(const u16* __restrict__ q, int ldq, int qpos0, const Seg& s0, const Seg& s1, int nseg, bool has_sink,
;                   float sinkl2, u16* __restrict__ out, int ldo, char* lds) {
;     ...
;   auto compute = [&](int i) {
;     const Seg& sg = (i < nt0) ? s0 : s1;
;     const int off = ((i < nt0) ? i : i - nt0) << 6;
;     f32x16 sa = zero16(), sb = zero16();
; #pragma unroll
;     for (int ks = 0; ks < NKS; ++ks) {
;       bf16x8 a0 = *(const bf16x8*)(Ks + r * KST + ks * 16 + 8 * h);
;       bf16x8 a1 = *(const bf16x8*)(Ks + (32 + r) * KST + ks * 16 + 8 * h);
;       sa = MFMA(a0, qf[ks], sa);
;       sb = MFMA(a1, qf[ks], sb);
;     }
;     ...
;   ATT_LOADX(0, kreg0, kreg1, vreg0);
;   ATT_LOADX(1, krgB0, krgB1, vrgB0);
;   for (int i = 0; i < NT; i += 2) {
;     __syncthreads();
;     ATT_STOREX(kreg0, kreg1, vreg0);
;     __syncthreads();
;     if (i + 2 < NT) ATT_LOADX(i + 2, kreg0, kreg1, vreg0);
;     compute(i);
.LBB0_599:
	s_or_b64 exec, exec, s[4:5]
	v_add_u32_e32 v4, 64, v117
	v_mov_b64_e32 v[2:3], s[12:13]
	v_mad_i64_i32 v[2:3], s[2:3], v4, s61, v[2:3]
	v_lshl_add_u64 v[2:3], v[2:3], 0, v[0:1]
	global_load_dwordx4 v[110:113], v[2:3], off offset:128
	s_movk_i32 s4, 0xd0
	v_lshlrev_b32_e32 v5, 1, v10
	v_lshlrev_b32_e32 v114, 2, v8
	v_lshrrev_b32_e32 v2, 2, v7
	v_mad_u32_u24 v130, v6, s4, v5
	v_and_b32_e32 v6, 64, v209
	v_and_or_b32 v2, v2, 3, v114
	s_add_u32 s23, s12, 0x80
	v_mul_lo_u32 v4, v116, s4
	v_xor_b32_e32 v5, 32, v209
	v_add_u32_e32 v6, 64, v6
	v_mul_u32_u24_e32 v2, 0xc0, v2
	v_lshlrev_b32_e32 v3, 1, v7
	s_addc_u32 s24, s13, 0
	v_lshl_add_u32 v121, v118, 1, v4
	v_mul_lo_u32 v4, v120, s4
	s_movk_i32 s2, 0xc0
	v_cmp_lt_i32_e64 s[4:5], v5, v6
	v_and_or_b32 v2, v3, 32, v2
	v_and_b32_e32 v3, 24, v11
	s_add_u32 s25, s8, 0x80
	v_lshl_add_u32 v129, v122, 1, v4
	v_mul_lo_u32 v4, v117, s2
	v_cndmask_b32_e64 v5, v209, v5, s[4:5]
	v_mov_b32_e32 v128, 0
	s_mov_b32 s22, 3
	s_addc_u32 s26, s9, 0
	v_ashrrev_i32_e32 v123, 31, v122
	v_mov_b32_e32 v124, v118
	v_mov_b32_e32 v125, v1
	v_cmp_lt_i32_e64 s[2:3], 7, v9
	v_mov_b32_e32 v126, v122
	v_mov_b32_e32 v127, v1
	v_lshlrev_b32_e32 v131, 2, v5
	v_mov_b32_e32 v134, 0xf149f2ca
	v_add_u32_e32 v132, v0, v4
	v_add_u32_e32 v133, v2, v3
	v_mov_b32_e32 v2, 0
	v_mov_b32_e32 v3, v128
	v_mov_b32_e32 v4, v128
	v_mov_b32_e32 v5, v128
	v_mov_b32_e32 v6, v128
	v_mov_b32_e32 v7, v128
	v_mov_b32_e32 v8, v128
	v_mov_b32_e32 v9, v128
	v_mov_b32_e32 v10, v128
	v_mov_b32_e32 v11, v128
	v_mov_b32_e32 v12, v128
	v_mov_b32_e32 v13, v128
	v_mov_b32_e32 v14, v128
	v_mov_b32_e32 v15, v128
	v_mov_b32_e32 v16, v128
	v_mov_b32_e32 v17, v128
	v_mov_b32_e32 v18, 0
	v_mov_b32_e32 v19, v128
	v_mov_b32_e32 v20, v128
	v_mov_b32_e32 v21, v128
	v_mov_b32_e32 v22, v128
	v_mov_b32_e32 v23, v128
	v_mov_b32_e32 v24, v128
	v_mov_b32_e32 v25, v128
	v_mov_b32_e32 v26, v128
	v_mov_b32_e32 v27, v128
	v_mov_b32_e32 v28, v128
	v_mov_b32_e32 v29, v128
	v_mov_b32_e32 v30, v128
	v_mov_b32_e32 v31, v128
	v_mov_b32_e32 v32, v128
	v_mov_b32_e32 v33, v128
	s_waitcnt vmcnt(0)
	s_barrier
	ds_write_b128 v121, v[90:93]
	s_and_saveexec_b64 s[4:5], s[0:1]
	ds_write_b128 v129, v[94:97]
	s_or_b64 exec, exec, s[4:5]
	s_waitcnt lgkmcnt(0)
	s_barrier
	ds_read_b128 v[34:37], v130
	ds_read_b128 v[38:41], v130 offset:6656
	ds_read_b128 v[42:45], v130 offset:32
	s_waitcnt lgkmcnt(2)
	v_mfma_f32_32x32x16_bf16 v[50:65], v[34:37], v[66:69], 0
	ds_read_b128 v[34:37], v130 offset:6688
	s_waitcnt lgkmcnt(2)
	v_mfma_f32_32x32x16_bf16 v[218:233], v[38:41], v[66:69], 0
	ds_read_b128 v[38:41], v130 offset:64
	s_waitcnt lgkmcnt(2)
	v_mfma_f32_32x32x16_bf16 v[50:65], v[42:45], v[70:73], v[50:65]
	ds_read_b128 v[42:45], v130 offset:6720
	s_waitcnt lgkmcnt(2)
	v_mfma_f32_32x32x16_bf16 v[218:233], v[34:37], v[70:73], v[218:233]
	ds_read_b128 v[34:37], v130 offset:96
	s_waitcnt lgkmcnt(2)
	v_mfma_f32_32x32x16_bf16 v[50:65], v[38:41], v[74:77], v[50:65]
	ds_read_b128 v[38:41], v130 offset:6752
	s_waitcnt lgkmcnt(2)
	v_mfma_f32_32x32x16_bf16 v[218:233], v[42:45], v[74:77], v[218:233]
	ds_read_b128 v[42:45], v130 offset:128
	s_waitcnt lgkmcnt(2)
	v_mfma_f32_32x32x16_bf16 v[50:65], v[34:37], v[78:81], v[50:65]
	ds_read_b128 v[34:37], v130 offset:6784
	s_waitcnt lgkmcnt(2)
	v_mfma_f32_32x32x16_bf16 v[218:233], v[38:41], v[78:81], v[218:233]
	ds_read_b128 v[38:41], v130 offset:160
	s_waitcnt lgkmcnt(2)
	v_mfma_f32_32x32x16_bf16 v[50:65], v[42:45], v[82:85], v[50:65]
	ds_read_b128 v[42:45], v130 offset:6816
	s_waitcnt lgkmcnt(2)
	v_mfma_f32_32x32x16_bf16 v[218:233], v[34:37], v[82:85], v[218:233]
	s_waitcnt lgkmcnt(1)
	v_mfma_f32_32x32x16_bf16 v[50:65], v[38:41], v[86:89], v[50:65]
	s_waitcnt lgkmcnt(0)
	v_mfma_f32_32x32x16_bf16 v[218:233], v[42:45], v[86:89], v[218:233]
	s_branch .LBB0_603

; #define MFMA(a, b, c) __builtin_amdgcn_mfma_f32_32x32x16_bf16((a), (b), (c), 0, 0, 0)
; DI int crow(int reg, int h) { return (reg & 3) + 8 * (reg >> 2) + 4 * h; }
; template <int DQK>
; DI void attn_tile(const u16* __restrict__ q, int ldq, int qpos0, const Seg& s0, const Seg& s1, int nseg, bool has_sink,
;                   float sinkl2, u16* __restrict__ out, int ldo, char* lds) {
;     ...
;   auto compute = [&](int i) {
;     const Seg& sg = (i < nt0) ? s0 : s1;
;     const int off = ((i < nt0) ? i : i - nt0) << 6;
;     f32x16 sa = zero16(), sb = zero16();
; #pragma unroll
;     for (int ks = 0; ks < NKS; ++ks) {
;       bf16x8 a0 = *(const bf16x8*)(Ks + r * KST + ks * 16 + 8 * h);
;       bf16x8 a1 = *(const bf16x8*)(Ks + (32 + r) * KST + ks * 16 + 8 * h);
;       sa = MFMA(a0, qf[ks], sa);
;       sb = MFMA(a1, qf[ks], sb);
;     }
;     if (sg.masked) {
;       const int qpos = qpos0 + qi;
;       const int kb = sg.pos0 + off;
; #pragma unroll
;       for (int g = 0; g < 16; ++g) {
;         int d0 = kb + crow(g, h) - qpos, d1 = d0 + 32;
;         if (d0 > 128 || d0 < -128) sa[g] = -INFINITY;
;         if (d1 > 128 || d1 < -128) sb[g] = -INFINITY;
;       }
;     }
;     float mx = sa[0];
; #pragma unroll
;     for (int g = 1; g < 16; ++g) mx = fmaxf(mx, sa[g]);
; #pragma unroll
;     for (int g = 0; g < 16; ++g) mx = fmaxf(mx, sb[g]);
;     mx = fmaxf(mx, __shfl_xor(mx, 32));
;     const float mn = fmaxf(m, mx);
;     const float alpha = __builtin_amdgcn_exp2f(m - mn);
;     m = mn;
;     float ps = 0.f;
; #pragma unroll
;     for (int g = 0; g < 16; ++g) { sa[g] = __builtin_amdgcn_exp2f(sa[g] - mn); ps += sa[g]; }
; #pragma unroll
;     for (int g = 0; g < 16; ++g) { sb[g] = __builtin_amdgcn_exp2f(sb[g] - mn); ps += sb[g]; }
;     l = l * alpha + ps;
; #pragma unroll
;     for (int g = 0; g < 16; ++g) { o0[g] *= alpha; o1[g] *= alpha; }
.LBB0_602:
	s_add_i32 s22, s22, 2
	s_cmpk_lt_u32 s27, 0x42
	ds_read_b128 v[34:37], v130
	ds_read_b128 v[38:41], v130 offset:6656
	ds_read_b128 v[42:45], v130 offset:32
	s_waitcnt lgkmcnt(2)
	v_mfma_f32_32x32x16_bf16 v[50:65], v[34:37], v[66:69], 0
	ds_read_b128 v[34:37], v130 offset:6688
	v_max3_f32 v137, v184, v185, v186
	v_max3_f32 v137, v137, v187, v188
	v_max3_f32 v137, v137, v189, v190
	v_max3_f32 v137, v137, v191, v192
	s_waitcnt lgkmcnt(2)
	v_mfma_f32_32x32x16_bf16 v[218:233], v[38:41], v[66:69], 0
	ds_read_b128 v[38:41], v130 offset:64
	v_max3_f32 v137, v137, v193, v194
	v_max3_f32 v137, v137, v195, v196
	v_max3_f32 v137, v137, v197, v198
	v_max3_f32 v137, v137, v199, v146
	s_waitcnt lgkmcnt(2)
	v_mfma_f32_32x32x16_bf16 v[50:65], v[42:45], v[70:73], v[50:65]
	ds_read_b128 v[42:45], v130 offset:6720
	v_max3_f32 v137, v137, v147, v148
	v_max3_f32 v137, v137, v149, v150
	v_max3_f32 v137, v137, v151, v152
	v_max3_f32 v137, v137, v153, v154
	s_waitcnt lgkmcnt(2)
	v_mfma_f32_32x32x16_bf16 v[218:233], v[34:37], v[70:73], v[218:233]
	ds_read_b128 v[34:37], v130 offset:96
	v_max3_f32 v137, v137, v155, v156
	v_max3_f32 v137, v137, v157, v158
	v_max3_f32 v137, v137, v159, v160
	v_max3_f32 v137, v137, v161, v161
	s_waitcnt lgkmcnt(2)
	v_mfma_f32_32x32x16_bf16 v[50:65], v[38:41], v[74:77], v[50:65]
	ds_read_b128 v[38:41], v130 offset:6752
	ds_bpermute_b32 v139, v131, v137
	s_waitcnt lgkmcnt(0)
	v_max3_f32 v134, v135, v137, v139
	v_sub_f32_e32 v141, v135, v134
	v_mfma_f32_32x32x16_bf16 v[218:233], v[42:45], v[74:77], v[218:233]
	ds_read_b128 v[42:45], v130 offset:128
	v_exp_f32_e32 v140, v141
	v_mov_b32_e32 v144, v134
	v_mov_b32_e32 v145, v134
	v_sub_f32_e32 v184, v184, v134
	v_mfma_f32_32x32x16_bf16 v[50:65], v[34:37], v[78:81], v[50:65]
	ds_read_b128 v[34:37], v130 offset:6784
	v_sub_f32_e32 v185, v185, v134
	v_sub_f32_e32 v186, v186, v134
	v_sub_f32_e32 v187, v187, v134
	v_sub_f32_e32 v188, v188, v134
	v_mfma_f32_32x32x16_bf16 v[218:233], v[38:41], v[78:81], v[218:233]
	ds_read_b128 v[38:41], v130 offset:160
	v_sub_f32_e32 v189, v189, v134
	v_sub_f32_e32 v190, v190, v134
	v_sub_f32_e32 v191, v191, v134
	v_exp_f32_e32 v184, v184
	s_waitcnt lgkmcnt(2)
	v_mfma_f32_32x32x16_bf16 v[50:65], v[42:45], v[82:85], v[50:65]
	ds_read_b128 v[42:45], v130 offset:6816
	v_sub_f32_e32 v192, v192, v134
	v_sub_f32_e32 v193, v193, v134
	v_sub_f32_e32 v194, v194, v134
	v_sub_f32_e32 v195, v195, v134
	s_waitcnt lgkmcnt(2)
	v_mfma_f32_32x32x16_bf16 v[218:233], v[34:37], v[82:85], v[218:233]
	v_exp_f32_e32 v185, v185
	v_sub_f32_e32 v196, v196, v134
	v_sub_f32_e32 v197, v197, v134
	v_sub_f32_e32 v198, v198, v134
	s_waitcnt lgkmcnt(1)
	v_mfma_f32_32x32x16_bf16 v[50:65], v[38:41], v[86:89], v[50:65]
	v_sub_f32_e32 v199, v199, v134
	v_exp_f32_e32 v186, v186
	v_sub_f32_e32 v146, v146, v134
	v_sub_f32_e32 v147, v147, v134
	s_waitcnt lgkmcnt(0)
	v_mfma_f32_32x32x16_bf16 v[218:233], v[42:45], v[86:89], v[218:233]
	ds_read_b64_tr_b16 v[46:47], v133 offset:13312
	ds_read_b64_tr_b16 v[48:49], v133 offset:14848
	ds_read_b64_tr_b16 v[200:201], v133 offset:13376
	ds_read_b64_tr_b16 v[202:203], v133 offset:14912
	ds_read_b64_tr_b16 v[204:205], v133 offset:16384
	ds_read_b64_tr_b16 v[206:207], v133 offset:17920
	ds_read_b64_tr_b16 v[234:235], v133 offset:16448
	ds_read_b64_tr_b16 v[236:237], v133 offset:17984
	v_sub_f32_e32 v148, v148, v134
	v_sub_f32_e32 v149, v149, v134
	v_exp_f32_e32 v187, v187
	v_sub_f32_e32 v150, v150, v134
	v_sub_f32_e32 v151, v151, v134
	v_sub_f32_e32 v152, v152, v134
	v_sub_f32_e32 v153, v153, v134
	v_exp_f32_e32 v188, v188
	v_mul_f32_e32 v33, v140, v33
	v_mul_f32_e32 v32, v140, v32
	v_mul_f32_e32 v31, v140, v31
	v_mul_f32_e32 v30, v140, v30
	v_exp_f32_e32 v189, v189
	v_mul_f32_e32 v29, v140, v29
	v_mul_f32_e32 v28, v140, v28
	v_mul_f32_e32 v27, v140, v27
	v_mul_f32_e32 v26, v140, v26
	v_exp_f32_e32 v190, v190
	v_mul_f32_e32 v25, v140, v25
	v_mul_f32_e32 v24, v140, v24
	v_mul_f32_e32 v23, v140, v23
	v_mul_f32_e32 v22, v140, v22
	v_exp_f32_e32 v191, v191
	v_mul_f32_e32 v21, v140, v21
	v_mul_f32_e32 v20, v140, v20
	v_mul_f32_e32 v19, v140, v19
	v_mul_f32_e32 v18, v140, v18
	v_exp_f32_e32 v192, v192
	v_sub_f32_e32 v154, v154, v134
	v_sub_f32_e32 v155, v155, v134
	v_sub_f32_e32 v156, v156, v134
	v_sub_f32_e32 v157, v157, v134
	v_sub_f32_e32 v158, v158, v134
	v_exp_f32_e32 v193, v193
	v_sub_f32_e32 v159, v159, v134
	v_sub_f32_e32 v160, v160, v134
	v_sub_f32_e32 v161, v161, v134
	v_mul_f32_e32 v17, v140, v17
	v_mul_f32_e32 v16, v140, v16
	v_exp_f32_e32 v194, v194
	v_mul_f32_e32 v15, v140, v15
	v_mul_f32_e32 v14, v140, v14
	v_mul_f32_e32 v13, v140, v13
	v_mul_f32_e32 v12, v140, v12
	v_mul_f32_e32 v11, v140, v11
	v_exp_f32_e32 v195, v195
	v_mul_f32_e32 v10, v140, v10
	v_mul_f32_e32 v9, v140, v9
	v_mul_f32_e32 v8, v140, v8
	v_mul_f32_e32 v7, v140, v7
	v_mul_f32_e32 v6, v140, v6
	v_exp_f32_e32 v196, v196
	v_mul_f32_e32 v5, v140, v5
	v_mul_f32_e32 v4, v140, v4
	v_mul_f32_e32 v3, v140, v3
	v_mul_f32_e32 v2, v140, v2
	v_add_f32_e32 v238, v184, v185
	v_exp_f32_e32 v197, v197
	v_add_f32_e32 v238, v238, v186
	v_add_f32_e32 v238, v238, v187
	v_add_f32_e32 v238, v238, v188
	v_add_f32_e32 v238, v238, v189
	v_add_f32_e32 v238, v238, v190
	v_exp_f32_e32 v198, v198
	v_add_f32_e32 v238, v238, v191
	v_cvt_pk_bf16_f32 v184, v184, v185
	v_cvt_pk_bf16_f32 v185, v186, v187
	v_cvt_pk_bf16_f32 v186, v188, v189
	v_cvt_pk_bf16_f32 v187, v190, v191
	v_exp_f32_e32 v199, v199
	s_nop 0
	s_waitcnt lgkmcnt(6)
; #define MFMA(a, b, c) __builtin_amdgcn_mfma_f32_32x32x16_bf16((a), (b), (c), 0, 0, 0)
; #define ATT_VTR(p) __builtin_bit_cast(s16x4, __builtin_amdgcn_ds_read_tr16_b64_v4i16((__attribute__((address_space(3))) v4i16_t*)(p)))
; template <int DQK>
; DI void attn_tile(const u16* __restrict__ q, int ldq, int qpos0, const Seg& s0, const Seg& s1, int nseg, bool has_sink,
;                   float sinkl2, u16* __restrict__ out, int ldo, char* lds) {
;     ...
;     for (int g = 0; g < 16; ++g) { sa[g] = __builtin_amdgcn_exp2f(sa[g] - mn); ps += sa[g]; }
; #pragma unroll
;     for (int g = 0; g < 16; ++g) { sb[g] = __builtin_amdgcn_exp2f(sb[g] - mn); ps += sb[g]; }
;     l = l * alpha + ps;
; #pragma unroll
;     for (int g = 0; g < 16; ++g) { o0[g] *= alpha; o1[g] *= alpha; }
; #pragma unroll
;     for (int kt = 0; kt < 2; ++kt) {
; #pragma unroll
;       for (int s = 0; s < 2; ++s) {
;         const f32x16& sv = kt == 0 ? sa : sb;
;         uint4 pu;
;         pu.x = pack2(sv[8 * s + 0], sv[8 * s + 1]); pu.y = pack2(sv[8 * s + 2], sv[8 * s + 3]);
;         pu.z = pack2(sv[8 * s + 4], sv[8 * s + 5]); pu.w = pack2(sv[8 * s + 6], sv[8 * s + 7]);
;         bf16x8 pf = __builtin_bit_cast(bf16x8, pu);
;         const lds_cptr vp = vp0 + (kt * 32 + 16 * s) * (VST * 2);
;         {
;           s16x4 lo = ATT_VTR(vp);
;           s16x4 hi = ATT_VTR(vp + 8 * VST * 2);
;           bf16x8 vf = __builtin_shufflevector(lo, hi, 0, 1, 2, 3, 4, 5, 6, 7);
;           o0 = MFMA(vf, pf, o0);
;         }
;         {
;           s16x4 lo = ATT_VTR(vp + 64);
;           s16x4 hi = ATT_VTR(vp + 8 * VST * 2 + 64);
;           bf16x8 vf = __builtin_shufflevector(lo, hi, 0, 1, 2, 3, 4, 5, 6, 7);
;           o1 = MFMA(vf, pf, o1);
;         }
;       }
;     }
;   };
;     ...
;   for (int i = 0; i < NT; i += 2) {
;     __syncthreads();
;     ATT_STOREX(kreg0, kreg1, vreg0);
;     __syncthreads();
;     if (i + 2 < NT) ATT_LOADX(i + 2, kreg0, kreg1, vreg0);
;     compute(i);
;     __syncthreads();
;     ATT_STOREX(krgB0, krgB1, vrgB0);
;     __syncthreads();
;     if (i + 3 < NT) ATT_LOADX(i + 3, krgB0, krgB1, vrgB0);
;     compute(i + 1);
	v_mfma_f32_32x32x16_bf16 v[18:33], v[46:49], v[184:187], v[18:33]
	ds_read_b64_tr_b16 v[46:47], v133 offset:19456
	ds_read_b64_tr_b16 v[48:49], v133 offset:20992
	s_waitcnt lgkmcnt(6)
	v_mfma_f32_32x32x16_bf16 v[2:17], v[200:203], v[184:187], v[2:17]
	ds_read_b64_tr_b16 v[200:201], v133 offset:19520
	ds_read_b64_tr_b16 v[202:203], v133 offset:21056
	v_exp_f32_e32 v146, v146
	v_add_f32_e32 v238, v238, v192
	v_add_f32_e32 v238, v238, v193
	v_exp_f32_e32 v147, v147
	v_add_f32_e32 v238, v238, v194
	v_add_f32_e32 v238, v238, v195
	v_exp_f32_e32 v148, v148
	v_add_f32_e32 v238, v238, v196
	v_add_f32_e32 v238, v238, v197
	v_exp_f32_e32 v149, v149
	v_add_f32_e32 v238, v238, v198
	v_add_f32_e32 v238, v238, v199
	v_exp_f32_e32 v150, v150
	v_cvt_pk_bf16_f32 v188, v192, v193
	v_cvt_pk_bf16_f32 v189, v194, v195
	v_exp_f32_e32 v151, v151
	v_cvt_pk_bf16_f32 v190, v196, v197
	v_cvt_pk_bf16_f32 v191, v198, v199
	v_exp_f32_e32 v152, v152
	v_exp_f32_e32 v153, v153
	s_nop 0
	s_waitcnt lgkmcnt(6)
	v_mfma_f32_32x32x16_bf16 v[18:33], v[204:207], v[188:191], v[18:33]
	ds_read_b64_tr_b16 v[204:205], v133 offset:22528
	ds_read_b64_tr_b16 v[206:207], v133 offset:24064
	s_waitcnt lgkmcnt(6)
	v_mfma_f32_32x32x16_bf16 v[2:17], v[234:237], v[188:191], v[2:17]
	ds_read_b64_tr_b16 v[234:235], v133 offset:22592
	ds_read_b64_tr_b16 v[236:237], v133 offset:24128
	v_exp_f32_e32 v154, v154
	v_add_f32_e32 v238, v238, v146
	v_add_f32_e32 v238, v238, v147
	v_exp_f32_e32 v155, v155
	v_add_f32_e32 v238, v238, v148
	v_add_f32_e32 v238, v238, v149
	v_exp_f32_e32 v156, v156
	v_add_f32_e32 v238, v238, v150
	v_add_f32_e32 v238, v238, v151
	v_exp_f32_e32 v157, v157
	v_add_f32_e32 v238, v238, v152
	v_add_f32_e32 v238, v238, v153
	v_exp_f32_e32 v158, v158
	v_cvt_pk_bf16_f32 v146, v146, v147
	v_cvt_pk_bf16_f32 v147, v148, v149
	v_exp_f32_e32 v159, v159
	v_cvt_pk_bf16_f32 v148, v150, v151
	v_cvt_pk_bf16_f32 v149, v152, v153
	v_exp_f32_e32 v160, v160
	v_exp_f32_e32 v161, v161
	s_nop 0
	s_waitcnt lgkmcnt(6)
	v_mfma_f32_32x32x16_bf16 v[18:33], v[46:49], v[146:149], v[18:33]
	s_waitcnt lgkmcnt(4)
	v_mfma_f32_32x32x16_bf16 v[2:17], v[200:203], v[146:149], v[2:17]
	v_add_f32_e32 v238, v238, v154
	v_add_f32_e32 v238, v238, v155
	v_add_f32_e32 v238, v238, v156
	v_add_f32_e32 v238, v238, v157
	v_add_f32_e32 v238, v238, v158
	v_add_f32_e32 v238, v238, v159
	v_add_f32_e32 v238, v238, v160
	v_add_f32_e32 v238, v238, v161
	v_cvt_pk_bf16_f32 v150, v154, v155
	v_cvt_pk_bf16_f32 v151, v156, v157
	v_cvt_pk_bf16_f32 v152, v158, v159
	v_cvt_pk_bf16_f32 v153, v160, v161
	s_nop 0
	s_waitcnt lgkmcnt(2)
	v_mfma_f32_32x32x16_bf16 v[18:33], v[204:207], v[150:153], v[18:33]
	s_waitcnt lgkmcnt(0)
	v_mfma_f32_32x32x16_bf16 v[2:17], v[234:237], v[150:153], v[2:17]
	v_fma_f32 v128, v136, v140, v238
	s_cbranch_scc0 .LBB0_727
.LBB0_603:
	s_barrier
	s_waitcnt vmcnt(0)
	ds_write_b128 v121, v[98:101]
	s_and_saveexec_b64 s[4:5], s[0:1]
	ds_write_b128 v129, v[106:109]
	s_or_b64 exec, exec, s[4:5]
	s_add_i32 s27, s22, -3
	s_cmpk_gt_u32 s27, 0x41
	s_waitcnt vmcnt(2)
	ds_write_b128 v132, v[102:105] offset:13312
	s_waitcnt lgkmcnt(0)
	s_barrier
	s_cbranch_scc1 .LBB0_617
	s_cmp_lt_u32 s27, 62
	s_cselect_b64 s[4:5], -1, 0
	s_and_b64 s[16:17], s[4:5], exec
	s_cselect_b32 s16, 0, 0x3ffffc0
	s_add_i32 s16, s16, s22
	s_lshl_b32 s16, s16, 6
	s_sub_i32 s28, s16, 64
	v_add_u32_e32 v34, s28, v116
	v_ashrrev_i32_e32 v35, 31, v34
	s_and_saveexec_b64 s[16:17], vcc
	s_xor_b64 s[16:17], exec, s[16:17]
	s_cbranch_execz .LBB0_609
	s_and_b64 s[18:19], s[4:5], exec
	s_cselect_b32 s19, s15, s11
	s_cselect_b32 s18, s14, s10
	v_lshlrev_b64 v[34:35], 6, v[34:35]
	v_lshl_add_u64 v[34:35], s[18:19], 0, v[34:35]
	s_movk_i32 s18, 0xff80
	v_lshl_add_u64 v[34:35], v[124:125], 1, v[34:35]
	s_mov_b32 s19, -1
	v_lshl_add_u64 v[36:37], v[34:35], 0, s[18:19]
	s_andn2_saveexec_b64 s[16:17], s[16:17]
	s_cbranch_execnz .LBB0_610

; #define MFMA(a, b, c) __builtin_amdgcn_mfma_f32_32x32x16_bf16((a), (b), (c), 0, 0, 0)
; DI int crow(int reg, int h) { return (reg & 3) + 8 * (reg >> 2) + 4 * h; }
; template <int DQK>
; DI void attn_tile(const u16* __restrict__ q, int ldq, int qpos0, const Seg& s0, const Seg& s1, int nseg, bool has_sink,
;                   float sinkl2, u16* __restrict__ out, int ldo, char* lds) {
;     ...
;   auto compute = [&](int i) {
;     const Seg& sg = (i < nt0) ? s0 : s1;
;     const int off = ((i < nt0) ? i : i - nt0) << 6;
;     f32x16 sa = zero16(), sb = zero16();
; #pragma unroll
;     for (int ks = 0; ks < NKS; ++ks) {
;       bf16x8 a0 = *(const bf16x8*)(Ks + r * KST + ks * 16 + 8 * h);
;       bf16x8 a1 = *(const bf16x8*)(Ks + (32 + r) * KST + ks * 16 + 8 * h);
;       sa = MFMA(a0, qf[ks], sa);
;       sb = MFMA(a1, qf[ks], sb);
;     }
;     if (sg.masked) {
;       const int qpos = qpos0 + qi;
;       const int kb = sg.pos0 + off;
; #pragma unroll
;       for (int g = 0; g < 16; ++g) {
;         int d0 = kb + crow(g, h) - qpos, d1 = d0 + 32;
;         if (d0 > 128 || d0 < -128) sa[g] = -INFINITY;
;         if (d1 > 128 || d1 < -128) sb[g] = -INFINITY;
;       }
;     }
;     float mx = sa[0];
; #pragma unroll
;     for (int g = 1; g < 16; ++g) mx = fmaxf(mx, sa[g]);
; #pragma unroll
;     for (int g = 0; g < 16; ++g) mx = fmaxf(mx, sb[g]);
;     mx = fmaxf(mx, __shfl_xor(mx, 32));
;     const float mn = fmaxf(m, mx);
;     const float alpha = __builtin_amdgcn_exp2f(m - mn);
;     m = mn;
;     float ps = 0.f;
; #pragma unroll
;     for (int g = 0; g < 16; ++g) { sa[g] = __builtin_amdgcn_exp2f(sa[g] - mn); ps += sa[g]; }
; #pragma unroll
;     for (int g = 0; g < 16; ++g) { sb[g] = __builtin_amdgcn_exp2f(sb[g] - mn); ps += sb[g]; }
;     l = l * alpha + ps;
; #pragma unroll
;     for (int g = 0; g < 16; ++g) { o0[g] *= alpha; o1[g] *= alpha; }
.LBB0_617:
	ds_read_b128 v[34:37], v130
	ds_read_b128 v[38:41], v130 offset:6656
	ds_read_b128 v[42:45], v130 offset:32
	s_waitcnt lgkmcnt(2)
	v_mfma_f32_32x32x16_bf16 v[184:199], v[34:37], v[66:69], 0
	ds_read_b128 v[34:37], v130 offset:6688
	v_max3_f32 v137, v50, v51, v52
	v_max3_f32 v137, v137, v53, v54
	v_max3_f32 v137, v137, v55, v56
	v_max3_f32 v137, v137, v57, v58
	s_waitcnt lgkmcnt(2)
	v_mfma_f32_32x32x16_bf16 v[146:161], v[38:41], v[66:69], 0
	ds_read_b128 v[38:41], v130 offset:64
	v_max3_f32 v137, v137, v59, v60
	v_max3_f32 v137, v137, v61, v62
	v_max3_f32 v137, v137, v63, v64
	v_max3_f32 v137, v137, v65, v218
	s_waitcnt lgkmcnt(2)
	v_mfma_f32_32x32x16_bf16 v[184:199], v[42:45], v[70:73], v[184:199]
	ds_read_b128 v[42:45], v130 offset:6720
	v_max3_f32 v137, v137, v219, v220
	v_max3_f32 v137, v137, v221, v222
	v_max3_f32 v137, v137, v223, v224
	v_max3_f32 v137, v137, v225, v226
	s_waitcnt lgkmcnt(2)
	v_mfma_f32_32x32x16_bf16 v[146:161], v[34:37], v[70:73], v[146:161]
	ds_read_b128 v[34:37], v130 offset:96
	v_max3_f32 v137, v137, v227, v228
	v_max3_f32 v137, v137, v229, v230
	v_max3_f32 v137, v137, v231, v232
	v_max3_f32 v137, v137, v233, v233
	s_waitcnt lgkmcnt(2)
	v_mfma_f32_32x32x16_bf16 v[184:199], v[38:41], v[74:77], v[184:199]
	ds_read_b128 v[38:41], v130 offset:6752
	ds_bpermute_b32 v139, v131, v137
	s_waitcnt lgkmcnt(0)
	v_max3_f32 v135, v134, v137, v139
	v_sub_f32_e32 v141, v134, v135
	v_mfma_f32_32x32x16_bf16 v[146:161], v[42:45], v[74:77], v[146:161]
	ds_read_b128 v[42:45], v130 offset:128
	v_exp_f32_e32 v140, v141
	v_mov_b32_e32 v144, v135
	v_mov_b32_e32 v145, v135
	v_sub_f32_e32 v50, v50, v135
	v_mfma_f32_32x32x16_bf16 v[184:199], v[34:37], v[78:81], v[184:199]
	ds_read_b128 v[34:37], v130 offset:6784
	v_sub_f32_e32 v51, v51, v135
	v_sub_f32_e32 v52, v52, v135
	v_sub_f32_e32 v53, v53, v135
	v_sub_f32_e32 v54, v54, v135
	v_mfma_f32_32x32x16_bf16 v[146:161], v[38:41], v[78:81], v[146:161]
	ds_read_b128 v[38:41], v130 offset:160
	v_sub_f32_e32 v55, v55, v135
	v_sub_f32_e32 v56, v56, v135
	v_sub_f32_e32 v57, v57, v135
	v_exp_f32_e32 v50, v50
	s_waitcnt lgkmcnt(2)
	v_mfma_f32_32x32x16_bf16 v[184:199], v[42:45], v[82:85], v[184:199]
	ds_read_b128 v[42:45], v130 offset:6816
	v_sub_f32_e32 v58, v58, v135
	v_sub_f32_e32 v59, v59, v135
	v_sub_f32_e32 v60, v60, v135
	v_sub_f32_e32 v61, v61, v135
	s_waitcnt lgkmcnt(2)
	v_mfma_f32_32x32x16_bf16 v[146:161], v[34:37], v[82:85], v[146:161]
	v_exp_f32_e32 v51, v51
	v_sub_f32_e32 v62, v62, v135
	v_sub_f32_e32 v63, v63, v135
	v_sub_f32_e32 v64, v64, v135
	s_waitcnt lgkmcnt(1)
	v_mfma_f32_32x32x16_bf16 v[184:199], v[38:41], v[86:89], v[184:199]
	v_sub_f32_e32 v65, v65, v135
	v_exp_f32_e32 v52, v52
	v_sub_f32_e32 v218, v218, v135
	v_sub_f32_e32 v219, v219, v135
	s_waitcnt lgkmcnt(0)
	v_mfma_f32_32x32x16_bf16 v[146:161], v[42:45], v[86:89], v[146:161]
	ds_read_b64_tr_b16 v[46:47], v133 offset:13312
	ds_read_b64_tr_b16 v[48:49], v133 offset:14848
	ds_read_b64_tr_b16 v[200:201], v133 offset:13376
	ds_read_b64_tr_b16 v[202:203], v133 offset:14912
	ds_read_b64_tr_b16 v[204:205], v133 offset:16384
	ds_read_b64_tr_b16 v[206:207], v133 offset:17920
	ds_read_b64_tr_b16 v[234:235], v133 offset:16448
	ds_read_b64_tr_b16 v[236:237], v133 offset:17984
	v_sub_f32_e32 v220, v220, v135
	v_sub_f32_e32 v221, v221, v135
	v_exp_f32_e32 v53, v53
	v_sub_f32_e32 v222, v222, v135
	v_sub_f32_e32 v223, v223, v135
	v_sub_f32_e32 v224, v224, v135
	v_sub_f32_e32 v225, v225, v135
	v_exp_f32_e32 v54, v54
	v_mul_f32_e32 v33, v140, v33
	v_mul_f32_e32 v32, v140, v32
	v_mul_f32_e32 v31, v140, v31
	v_mul_f32_e32 v30, v140, v30
	v_exp_f32_e32 v55, v55
	v_mul_f32_e32 v29, v140, v29
	v_mul_f32_e32 v28, v140, v28
	v_mul_f32_e32 v27, v140, v27
	v_mul_f32_e32 v26, v140, v26
	v_exp_f32_e32 v56, v56
	v_mul_f32_e32 v25, v140, v25
	v_mul_f32_e32 v24, v140, v24
	v_mul_f32_e32 v23, v140, v23
	v_mul_f32_e32 v22, v140, v22
	v_exp_f32_e32 v57, v57
	v_mul_f32_e32 v21, v140, v21
	v_mul_f32_e32 v20, v140, v20
	v_mul_f32_e32 v19, v140, v19
	v_mul_f32_e32 v18, v140, v18
	v_exp_f32_e32 v58, v58
	v_sub_f32_e32 v226, v226, v135
	v_sub_f32_e32 v227, v227, v135
	v_sub_f32_e32 v228, v228, v135
	v_sub_f32_e32 v229, v229, v135
	v_sub_f32_e32 v230, v230, v135
	v_exp_f32_e32 v59, v59
	v_sub_f32_e32 v231, v231, v135
	v_sub_f32_e32 v232, v232, v135
	v_sub_f32_e32 v233, v233, v135
	v_mul_f32_e32 v17, v140, v17
	v_mul_f32_e32 v16, v140, v16
	v_exp_f32_e32 v60, v60
	v_mul_f32_e32 v15, v140, v15
	v_mul_f32_e32 v14, v140, v14
	v_mul_f32_e32 v13, v140, v13
	v_mul_f32_e32 v12, v140, v12
	v_mul_f32_e32 v11, v140, v11
	v_exp_f32_e32 v61, v61
	v_mul_f32_e32 v10, v140, v10
	v_mul_f32_e32 v9, v140, v9
	v_mul_f32_e32 v8, v140, v8
	v_mul_f32_e32 v7, v140, v7
	v_mul_f32_e32 v6, v140, v6
	v_exp_f32_e32 v62, v62
	v_mul_f32_e32 v5, v140, v5
	v_mul_f32_e32 v4, v140, v4
	v_mul_f32_e32 v3, v140, v3
	v_mul_f32_e32 v2, v140, v2
	v_add_f32_e32 v238, v50, v51
	v_exp_f32_e32 v63, v63
	v_add_f32_e32 v238, v238, v52
	v_add_f32_e32 v238, v238, v53
	v_add_f32_e32 v238, v238, v54
	v_add_f32_e32 v238, v238, v55
	v_add_f32_e32 v238, v238, v56
	v_exp_f32_e32 v64, v64
	v_add_f32_e32 v238, v238, v57
	v_cvt_pk_bf16_f32 v50, v50, v51
	v_cvt_pk_bf16_f32 v51, v52, v53
	v_cvt_pk_bf16_f32 v52, v54, v55
	v_cvt_pk_bf16_f32 v53, v56, v57
	v_exp_f32_e32 v65, v65
	s_nop 0
	s_waitcnt lgkmcnt(6)
; #define MFMA(a, b, c) __builtin_amdgcn_mfma_f32_32x32x16_bf16((a), (b), (c), 0, 0, 0)
; #define ATT_VTR(p) __builtin_bit_cast(s16x4, __builtin_amdgcn_ds_read_tr16_b64_v4i16((__attribute__((address_space(3))) v4i16_t*)(p)))
; template <int DQK>
; DI void attn_tile(const u16* __restrict__ q, int ldq, int qpos0, const Seg& s0, const Seg& s1, int nseg, bool has_sink,
;                   float sinkl2, u16* __restrict__ out, int ldo, char* lds) {
;     ...
; #pragma unroll
;     for (int kt = 0; kt < 2; ++kt) {
; #pragma unroll
;       for (int s = 0; s < 2; ++s) {
;         const f32x16& sv = kt == 0 ? sa : sb;
;         uint4 pu;
;         pu.x = pack2(sv[8 * s + 0], sv[8 * s + 1]); pu.y = pack2(sv[8 * s + 2], sv[8 * s + 3]);
;         pu.z = pack2(sv[8 * s + 4], sv[8 * s + 5]); pu.w = pack2(sv[8 * s + 6], sv[8 * s + 7]);
;         bf16x8 pf = __builtin_bit_cast(bf16x8, pu);
;         const lds_cptr vp = vp0 + (kt * 32 + 16 * s) * (VST * 2);
;         {
;           s16x4 lo = ATT_VTR(vp);
;           s16x4 hi = ATT_VTR(vp + 8 * VST * 2);
;           bf16x8 vf = __builtin_shufflevector(lo, hi, 0, 1, 2, 3, 4, 5, 6, 7);
;           o0 = MFMA(vf, pf, o0);
;         }
;         {
;           s16x4 lo = ATT_VTR(vp + 64);
;           s16x4 hi = ATT_VTR(vp + 8 * VST * 2 + 64);
;           bf16x8 vf = __builtin_shufflevector(lo, hi, 0, 1, 2, 3, 4, 5, 6, 7);
;           o1 = MFMA(vf, pf, o1);
;         }
;       }
;     }
;   };
;     ...
;   for (int i = 0; i < NT; i += 2) {
;     __syncthreads();
;     ATT_STOREX(kreg0, kreg1, vreg0);
;     __syncthreads();
;     if (i + 2 < NT) ATT_LOADX(i + 2, kreg0, kreg1, vreg0);
;     compute(i);
;     __syncthreads();
;     ATT_STOREX(krgB0, krgB1, vrgB0);
;     __syncthreads();
;     if (i + 3 < NT) ATT_LOADX(i + 3, krgB0, krgB1, vrgB0);
;     compute(i + 1);
	v_mfma_f32_32x32x16_bf16 v[18:33], v[46:49], v[50:53], v[18:33]
	ds_read_b64_tr_b16 v[46:47], v133 offset:19456
	ds_read_b64_tr_b16 v[48:49], v133 offset:20992
	s_waitcnt lgkmcnt(6)
	v_mfma_f32_32x32x16_bf16 v[2:17], v[200:203], v[50:53], v[2:17]
	ds_read_b64_tr_b16 v[200:201], v133 offset:19520
	ds_read_b64_tr_b16 v[202:203], v133 offset:21056
	v_exp_f32_e32 v218, v218
	v_add_f32_e32 v238, v238, v58
	v_add_f32_e32 v238, v238, v59
	v_exp_f32_e32 v219, v219
	v_add_f32_e32 v238, v238, v60
	v_add_f32_e32 v238, v238, v61
	v_exp_f32_e32 v220, v220
	v_add_f32_e32 v238, v238, v62
	v_add_f32_e32 v238, v238, v63
	v_exp_f32_e32 v221, v221
	v_add_f32_e32 v238, v238, v64
	v_add_f32_e32 v238, v238, v65
	v_exp_f32_e32 v222, v222
	v_cvt_pk_bf16_f32 v54, v58, v59
	v_cvt_pk_bf16_f32 v55, v60, v61
	v_exp_f32_e32 v223, v223
	v_cvt_pk_bf16_f32 v56, v62, v63
	v_cvt_pk_bf16_f32 v57, v64, v65
	v_exp_f32_e32 v224, v224
	v_exp_f32_e32 v225, v225
	s_nop 0
	s_waitcnt lgkmcnt(6)
	v_mfma_f32_32x32x16_bf16 v[18:33], v[204:207], v[54:57], v[18:33]
	ds_read_b64_tr_b16 v[204:205], v133 offset:22528
	ds_read_b64_tr_b16 v[206:207], v133 offset:24064
	s_waitcnt lgkmcnt(6)
	v_mfma_f32_32x32x16_bf16 v[2:17], v[234:237], v[54:57], v[2:17]
	ds_read_b64_tr_b16 v[234:235], v133 offset:22592
	ds_read_b64_tr_b16 v[236:237], v133 offset:24128
	v_exp_f32_e32 v226, v226
	v_add_f32_e32 v238, v238, v218
	v_add_f32_e32 v238, v238, v219
	v_exp_f32_e32 v227, v227
	v_add_f32_e32 v238, v238, v220
	v_add_f32_e32 v238, v238, v221
	v_exp_f32_e32 v228, v228
	v_add_f32_e32 v238, v238, v222
	v_add_f32_e32 v238, v238, v223
	v_exp_f32_e32 v229, v229
	v_add_f32_e32 v238, v238, v224
	v_add_f32_e32 v238, v238, v225
	v_exp_f32_e32 v230, v230
	v_cvt_pk_bf16_f32 v218, v218, v219
	v_cvt_pk_bf16_f32 v219, v220, v221
	v_exp_f32_e32 v231, v231
	v_cvt_pk_bf16_f32 v220, v222, v223
	v_cvt_pk_bf16_f32 v221, v224, v225
	v_exp_f32_e32 v232, v232
	v_exp_f32_e32 v233, v233
	s_nop 0
	s_waitcnt lgkmcnt(6)
	v_mfma_f32_32x32x16_bf16 v[18:33], v[46:49], v[218:221], v[18:33]
	s_waitcnt lgkmcnt(4)
	v_mfma_f32_32x32x16_bf16 v[2:17], v[200:203], v[218:221], v[2:17]
	v_add_f32_e32 v238, v238, v226
	v_add_f32_e32 v238, v238, v227
	v_add_f32_e32 v238, v238, v228
	v_add_f32_e32 v238, v238, v229
	v_add_f32_e32 v238, v238, v230
	v_add_f32_e32 v238, v238, v231
	v_add_f32_e32 v238, v238, v232
	v_add_f32_e32 v238, v238, v233
	v_cvt_pk_bf16_f32 v222, v226, v227
	v_cvt_pk_bf16_f32 v223, v228, v229
	v_cvt_pk_bf16_f32 v224, v230, v231
	v_cvt_pk_bf16_f32 v225, v232, v233
	s_nop 0
	s_waitcnt lgkmcnt(2)
	v_mfma_f32_32x32x16_bf16 v[18:33], v[204:207], v[222:225], v[18:33]
	s_waitcnt lgkmcnt(0)
	v_mfma_f32_32x32x16_bf16 v[2:17], v[234:237], v[222:225], v[2:17]
	v_fma_f32 v136, v128, v140, v238
	s_waitcnt lgkmcnt(0)
	s_barrier
	s_waitcnt vmcnt(0)
	ds_write_b128 v121, v[90:93]
	s_and_saveexec_b64 s[4:5], s[0:1]
	ds_write_b128 v129, v[94:97]
	s_or_b64 exec, exec, s[4:5]
	s_cmp_gt_u32 s27, 64
	ds_write_b128 v132, v[110:113] offset:13312
	s_waitcnt lgkmcnt(0)
	s_barrier
	s_cbranch_scc1 .LBB0_602
	s_cmp_lt_u32 s27, 61
	s_cselect_b64 s[4:5], -1, 0
	s_and_b64 s[16:17], s[4:5], exec
	s_cselect_b32 s16, 0, 0x3ffffc0
	s_add_i32 s16, s16, s22
	s_lshl_b32 s28, s16, 6
	v_add_u32_e32 v36, s28, v116
	v_ashrrev_i32_e32 v37, 31, v36
	s_and_saveexec_b64 s[16:17], vcc
	s_xor_b64 s[16:17], exec, s[16:17]
	s_cbranch_execz .LBB0_623
	s_and_b64 s[18:19], s[4:5], exec
	s_cselect_b32 s19, s15, s11
	s_cselect_b32 s18, s14, s10
	v_lshlrev_b64 v[36:37], 6, v[36:37]
	v_lshl_add_u64 v[36:37], s[18:19], 0, v[36:37]
	s_movk_i32 s18, 0xff80
	v_lshl_add_u64 v[36:37], v[124:125], 1, v[36:37]
	s_mov_b32 s19, -1
	v_lshl_add_u64 v[38:39], v[36:37], 0, s[18:19]
	s_andn2_saveexec_b64 s[16:17], s[16:17]
	s_cbranch_execnz .LBB0_624
